# LRU scan section: batched LDS reads, recurrence in registers, batched writes
# speedup vs baseline: 1.0069x; 1.0045x over previous
.LBB0_1094:
	s_lshl_b32 s15, s11, 7
	s_mov_b64 s[0:1], s[22:23]
	v_add_u32_e32 v82, s15, v130
	s_add_u32 s8, s0, 0x7a00000
	v_max_i32_e32 v56, 3, v82
	s_addc_u32 s9, s1, 0
	v_add_u32_e32 v112, -3, v56
	v_lshl_add_u64 v[56:57], s[20:21], 0, v[112:113]
	v_mov_b64_e32 v[72:73], s[8:9]
	v_mad_u64_u32 v[58:59], s[0:1], v56, s33, v[72:73]
	v_mad_i32_i24 v59, v57, s33, v59
	v_mov_b32_e32 v107, v113
	v_lshl_add_u64 v[56:57], v[58:59], 0, v[106:107]
	v_add_co_u32_e32 v56, vcc, s74, v56
	v_max_i32_e32 v74, -1, v82
	s_nop 0
	v_addc_co_u32_e32 v57, vcc, 0, v57, vcc
	s_waitcnt vmcnt(16)
	v_mov_b32_e32 v64, v228
	v_mov_b32_e32 v65, v229
	v_mov_b32_e32 v66, v230
	v_mov_b32_e32 v67, v231
	v_or_b32_e32 v56, 1, v82
	v_max_i32_e32 v56, 3, v56
	v_add_u32_e32 v112, -3, v56
	v_lshl_add_u64 v[56:57], s[20:21], 0, v[112:113]
	v_mad_u64_u32 v[58:59], s[0:1], v56, s33, v[72:73]
	v_mad_i32_i24 v59, v57, s33, v59
	v_lshl_add_u64 v[56:57], v[58:59], 0, v[106:107]
	v_add_co_u32_e32 v56, vcc, s74, v56
	v_cmp_lt_i32_e64 s[2:3], 2, v82
	s_nop 0
	v_addc_co_u32_e32 v57, vcc, 0, v57, vcc
	v_mov_b32_e32 v68, v232
	v_mov_b32_e32 v69, v233
	v_mov_b32_e32 v70, v234
	v_mov_b32_e32 v71, v235
	v_max_i32_e32 v56, 1, v82
	v_add_u32_e32 v112, -1, v56
	v_lshl_add_u64 v[56:57], s[20:21], 0, v[112:113]
	v_max_i32_e32 v112, 0, v82
	v_lshl_add_u64 v[60:61], s[20:21], 0, v[112:113]
	v_add_u32_e32 v112, 1, v74
	v_lshl_add_u64 v[74:75], s[20:21], 0, v[112:113]
	v_mad_u64_u32 v[58:59], s[0:1], v56, s33, v[72:73]
	v_mad_u64_u32 v[62:63], s[0:1], v60, s33, v[72:73]
	v_mad_u64_u32 v[72:73], s[0:1], v74, s33, v[72:73]
	v_mad_i32_i24 v73, v75, s33, v73
	v_lshl_add_u64 v[72:73], v[72:73], 0, v[106:107]
	v_add_co_u32_e64 v72, s[0:1], s74, v72
	v_mad_i32_i24 v59, v57, s33, v59
	s_nop 0
	v_addc_co_u32_e64 v73, s[0:1], 0, v73, s[0:1]
	v_mov_b32_e32 v72, v236
	v_mov_b32_e32 v73, v237
	v_mov_b32_e32 v74, v238
	v_mov_b32_e32 v75, v239
	v_lshl_add_u64 v[56:57], v[58:59], 0, v[106:107]
	v_add_co_u32_e32 v56, vcc, s74, v56
	v_mad_i32_i24 v63, v61, s33, v63
	s_nop 0
	v_addc_co_u32_e32 v57, vcc, 0, v57, vcc
	v_lshl_add_u64 v[60:61], v[62:63], 0, v[106:107]
	v_add_co_u32_e32 v60, vcc, s74, v60
	v_mov_b32_e32 v56, v240
	v_mov_b32_e32 v57, v241
	v_mov_b32_e32 v58, v242
	v_mov_b32_e32 v59, v243
	s_nop 0
	v_addc_co_u32_e32 v61, vcc, 0, v61, vcc
	v_mov_b32_e32 v60, v244
	v_mov_b32_e32 v61, v245
	v_mov_b32_e32 v62, v246
	v_mov_b32_e32 v63, v247
	v_cmp_lt_i32_e32 vcc, -2, v82
	v_cmp_lt_i32_e64 s[0:1], -1, v82
	s_nop 0
	v_cndmask_b32_e64 v83, 0, v67, s[2:3]
	v_cndmask_b32_e64 v64, 0, v64, s[2:3]
	s_nop 0
	v_cndmask_b32_e32 v107, 0, v72, vcc
	v_cndmask_b32_e32 v109, 0, v73, vcc
	v_cndmask_b32_e32 v112, 0, v74, vcc
	v_cndmask_b32_e32 v151, 0, v75, vcc
	v_cmp_lt_i32_e32 vcc, 1, v82
	v_lshlrev_b32_e32 v74, 16, v64
	v_lshlrev_b32_e32 v72, 16, v83
	v_cndmask_b32_e32 v67, 0, v68, vcc
	v_lshlrev_b32_e32 v75, 16, v67
	v_pk_mul_f32 v[76:77], v[104:105], v[74:75]
	v_cndmask_b32_e32 v84, 0, v71, vcc
	v_add_f32_e32 v68, v48, v76
	v_add_f32_e32 v74, v68, v77
	v_and_b32_e32 v77, 0xffff0000, v67
	v_and_b32_e32 v76, 0xffff0000, v64
	v_pk_mul_f32 v[80:81], v[40:41], v[76:77]
	v_cndmask_b32_e64 v67, 0, v65, s[2:3]
	v_add_f32_e32 v64, v49, v80
	v_cndmask_b32_e32 v71, 0, v69, vcc
	v_add_f32_e32 v152, v64, v81
	v_lshlrev_b32_e32 v65, 16, v71
	v_lshlrev_b32_e32 v64, 16, v67
	v_pk_mul_f32 v[68:69], v[100:101], v[64:65]
	v_lshlrev_b32_e32 v73, 16, v84
	v_add_f32_e32 v64, v50, v68
	v_add_f32_e32 v64, v64, v69
	v_and_b32_e32 v69, 0xffff0000, v71
	v_and_b32_e32 v68, 0xffff0000, v67
	v_pk_mul_f32 v[78:79], v[92:93], v[72:73]
	v_pk_mul_f32 v[80:81], v[42:43], v[68:69]
	v_add_f32_e32 v72, v54, v78
	v_add_f32_e32 v67, v51, v80
	v_cndmask_b32_e64 v78, 0, v66, s[2:3]
	v_cndmask_b32_e32 v80, 0, v70, vcc
	v_add_f32_e32 v153, v67, v81
	v_lshlrev_b32_e32 v67, 16, v80
	v_lshlrev_b32_e32 v66, 16, v78
	v_pk_mul_f32 v[70:71], v[96:97], v[66:67]
	v_cmp_lt_i32_e32 vcc, 0, v82
	v_add_f32_e32 v66, v52, v70
	v_add_f32_e32 v66, v66, v71
	v_and_b32_e32 v71, 0xffff0000, v80
	v_and_b32_e32 v70, 0xffff0000, v78
	v_pk_mul_f32 v[80:81], v[36:37], v[70:71]
	v_add_f32_e32 v72, v72, v79
	v_add_f32_e32 v78, v53, v80
	v_add_f32_e32 v154, v78, v81
	v_and_b32_e32 v79, 0xffff0000, v84
	v_and_b32_e32 v78, 0xffff0000, v83
	s_nop 0
	v_cndmask_b32_e64 v60, 0, v60, s[0:1]
	v_cndmask_b32_e32 v56, 0, v56, vcc
	v_pk_mul_f32 v[80:81], v[38:39], v[78:79]
	v_lshlrev_b32_e32 v84, 16, v56
	v_lshlrev_b32_e32 v85, 16, v60
	v_add_f32_e32 v80, v55, v80
	v_cndmask_b32_e64 v156, 0, v63, s[0:1]
	v_cndmask_b32_e32 v59, 0, v59, vcc
	v_pk_mul_f32 v[86:87], v[102:103], v[84:85]
	v_add_f32_e32 v155, v80, v81
	v_lshlrev_b32_e32 v80, 16, v59
	v_lshlrev_b32_e32 v81, 16, v156
	v_add_f32_e32 v63, v74, v86
	v_pk_mul_f32 v[82:83], v[90:91], v[80:81]
	v_add_f32_e32 v74, v63, v87
	v_and_b32_e32 v87, 0xffff0000, v60
	v_and_b32_e32 v86, 0xffff0000, v56
	v_add_f32_e32 v72, v72, v82
	v_pk_mul_f32 v[110:111], v[44:45], v[86:87]
	v_cndmask_b32_e64 v63, 0, v61, s[0:1]
	v_cndmask_b32_e32 v82, 0, v57, vcc
	v_add_f32_e32 v56, v152, v110
	v_lshlrev_b32_e32 v60, 16, v82
	v_lshlrev_b32_e32 v61, 16, v63
	v_add_f32_e32 v157, v56, v111
	v_pk_mul_f32 v[56:57], v[98:99], v[60:61]
	v_and_b32_e32 v111, 0xffff0000, v63
	v_add_f32_e32 v56, v64, v56
	v_and_b32_e32 v110, 0xffff0000, v82
	v_add_f32_e32 v64, v56, v57
	v_pk_mul_f32 v[56:57], v[46:47], v[110:111]
	v_cndmask_b32_e64 v82, 0, v62, s[0:1]
	v_cndmask_b32_e32 v58, 0, v58, vcc
	v_add_f32_e32 v56, v153, v56
	v_lshlrev_b32_e32 v62, 16, v58
	v_lshlrev_b32_e32 v63, 16, v82
	v_add_f32_e32 v158, v56, v57
	v_pk_mul_f32 v[56:57], v[94:95], v[62:63]
	v_and_b32_e32 v153, 0xffff0000, v82
	v_add_f32_e32 v56, v66, v56
	v_and_b32_e32 v152, 0xffff0000, v58
	v_add_f32_e32 v66, v56, v57
	v_pk_mul_f32 v[56:57], v[32:33], v[152:153]
	v_add_f32_e32 v72, v72, v83
	v_add_f32_e32 v56, v154, v56
	v_and_b32_e32 v83, 0xffff0000, v156
	v_and_b32_e32 v82, 0xffff0000, v59
	v_add_f32_e32 v58, v56, v57
	v_pk_mul_f32 v[56:57], v[34:35], v[82:83]
	s_add_u32 s0, s12, s15
	v_add_f32_e32 v56, v155, v56
	v_add_f32_e32 v59, v56, v57
	v_cvt_pk_bf16_f32 v56, v74, v157
	v_cvt_pk_bf16_f32 v57, v64, v158
	v_cvt_pk_bf16_f32 v58, v66, v58
	v_cvt_pk_bf16_f32 v59, v72, v59
	ds_write_b128 v142, v[56:59] offset:18432
	v_pk_mov_b32 v[56:57], v[74:75], v[84:85] op_sel:[1,0]
	v_and_b32_e32 v59, 0xffff0000, v107
	v_pk_mul_f32 v[56:57], v[104:105], v[56:57]
	v_and_b32_e32 v75, 0xffff0000, v151
	v_add_f32_e32 v56, v48, v56
	v_add_f32_e32 v58, v56, v57
	v_pk_mov_b32 v[56:57], v[76:77], v[86:87] op_sel:[1,0]
	s_addc_u32 s1, s13, 0
	v_pk_mul_f32 v[56:57], v[40:41], v[56:57]
	s_mulk_i32 s1, 0x2400
	v_add_f32_e32 v56, v49, v56
	v_add_f32_e32 v64, v56, v57
	v_pk_mov_b32 v[56:57], v[64:65], v[60:61] op_sel:[1,0]
	v_lshlrev_b32_e32 v65, 16, v109
	v_pk_mul_f32 v[56:57], v[100:101], v[56:57]
	s_mul_hi_u32 s2, s0, 0x2400
	v_add_f32_e32 v56, v50, v56
	v_add_f32_e32 v60, v56, v57
	v_pk_mov_b32 v[56:57], v[68:69], v[110:111] op_sel:[1,0]
	v_lshlrev_b32_e32 v69, 16, v112
	v_pk_mul_f32 v[56:57], v[42:43], v[56:57]
	s_add_i32 s2, s2, s1
	v_add_f32_e32 v56, v51, v56
	v_add_f32_e32 v68, v56, v57
	v_pk_mov_b32 v[56:57], v[66:67], v[62:63] op_sel:[1,0]
	v_and_b32_e32 v67, 0xffff0000, v109
	v_pk_mul_f32 v[56:57], v[96:97], v[56:57]
	v_mov_b32_e32 v66, v111
	v_add_f32_e32 v56, v52, v56
	v_add_f32_e32 v62, v56, v57
	v_pk_mov_b32 v[56:57], v[70:71], v[152:153] op_sel:[1,0]
	v_and_b32_e32 v71, 0xffff0000, v112
	v_pk_mul_f32 v[56:57], v[36:37], v[56:57]
	v_mov_b32_e32 v70, v153
	v_add_f32_e32 v56, v53, v56
	v_add_f32_e32 v72, v56, v57
	v_pk_mov_b32 v[56:57], v[72:73], v[80:81] op_sel:[1,0]
	v_lshlrev_b32_e32 v73, 16, v151
	v_pk_mul_f32 v[56:57], v[92:93], v[56:57]
	v_add_u32_e32 v80, v132, v131
	v_add_f32_e32 v56, v54, v56
	v_add_f32_e32 v74, v56, v57
	v_pk_mov_b32 v[56:57], v[78:79], v[82:83] op_sel:[1,0]
	s_mulk_i32 s0, 0x2400
	v_pk_mul_f32 v[56:57], v[38:39], v[56:57]
	s_add_u32 s0, s8, s0
	v_add_f32_e32 v56, v55, v56
	v_add_f32_e32 v76, v56, v57
	v_lshlrev_b32_e32 v57, 16, v107
	v_mov_b32_e32 v56, v85
	v_pk_mul_f32 v[56:57], v[102:103], v[56:57]
	s_addc_u32 s1, s9, s2
	v_add_f32_e32 v56, v58, v56
	v_mov_b32_e32 v58, v87
	v_add_f32_e32 v77, v56, v57
	v_pk_mul_f32 v[56:57], v[44:45], v[58:59]
	s_add_u32 s0, s0, s14
	v_add_f32_e32 v56, v64, v56
	v_mov_b32_e32 v64, v61
	v_add_f32_e32 v58, v56, v57
	v_pk_mul_f32 v[56:57], v[98:99], v[64:65]
	s_addc_u32 s1, s1, 0
	v_add_f32_e32 v56, v60, v56
	v_add_f32_e32 v59, v56, v57
	v_pk_mul_f32 v[56:57], v[46:47], v[66:67]
	v_mov_b32_e32 v109, v113
	v_add_f32_e32 v56, v68, v56
	v_mov_b32_e32 v68, v63
	v_add_f32_e32 v60, v56, v57
	v_pk_mul_f32 v[56:57], v[94:95], v[68:69]
	s_nop 0
	v_add_f32_e32 v56, v62, v56
	v_add_f32_e32 v61, v56, v57
	v_pk_mul_f32 v[56:57], v[32:33], v[70:71]
	s_nop 0
	v_add_f32_e32 v56, v72, v56
	v_mov_b32_e32 v72, v81
	v_add_f32_e32 v62, v56, v57
	v_pk_mul_f32 v[56:57], v[90:91], v[72:73]
	s_nop 0
	v_add_f32_e32 v56, v74, v56
	v_mov_b32_e32 v74, v83
	v_add_f32_e32 v63, v56, v57
	v_pk_mul_f32 v[56:57], v[34:35], v[74:75]
	s_nop 0
	v_add_f32_e32 v56, v76, v56
	v_add_f32_e32 v64, v56, v57
	v_cvt_pk_bf16_f32 v56, v77, v58
	v_cvt_pk_bf16_f32 v57, v59, v60
	v_cvt_pk_bf16_f32 v58, v61, v62
	v_cvt_pk_bf16_f32 v59, v63, v64
	ds_write_b128 v143, v[56:59] offset:18432
	s_waitcnt lgkmcnt(0)
	s_barrier
	s_add_i32 s98, s11, 1
	s_min_u32 s98, s98, 15
	s_lshl_b32 s98, s98, 7
	v_add_u32_e32 v172, s98, v130
	v_add_u32_e32 v173, 0x7a01c00, v106
	v_add_u32_e32 v174, -3, v172
	v_max_i32_e32 v174, 0, v174
	v_add_u32_e32 v174, s20, v174
	v_mad_u32_u24 v174, v174, s33, v173
	global_load_dwordx4 v[228:231], v174, s[22:23]
	v_add_u32_e32 v175, -2, v172
	v_max_i32_e32 v175, 0, v175
	v_add_u32_e32 v175, s20, v175
	v_mad_u32_u24 v175, v175, s33, v173
	global_load_dwordx4 v[232:235], v175, s[22:23]
	v_add_u32_e32 v176, 1, v172
	v_max_i32_e32 v176, 0, v176
	v_add_u32_e32 v176, s20, v176
	v_mad_u32_u24 v176, v176, s33, v173
	global_load_dwordx4 v[236:239], v176, s[22:23]
	v_add_u32_e32 v177, -1, v172
	v_max_i32_e32 v177, 0, v177
	v_add_u32_e32 v177, s20, v177
	v_mad_u32_u24 v177, v177, s33, v173
	global_load_dwordx4 v[240:243], v177, s[22:23]
	v_add_u32_e32 v178, 0, v172
	v_max_i32_e32 v178, 0, v178
	v_add_u32_e32 v178, s20, v178
	v_mad_u32_u24 v178, v178, s33, v173
	global_load_dwordx4 v[244:247], v178, s[22:23]
	ds_read_b128 v[56:59], v80 offset:18432
	ds_read_b128 v[60:63], v144
	ds_read_b128 v[68:71], v144 offset:2304
	ds_read_b128 v[76:79], v144 offset:4608
	ds_read_b128 v[72:75], v144 offset:11520
	s_waitcnt lgkmcnt(1)
	v_mfma_f32_16x16x32_bf16 v[152:155], v[76:79], v[56:59], 0
	ds_read_b128 v[76:79], v144 offset:13824
	ds_read_b128 v[64:67], v144 offset:9216
	s_waitcnt lgkmcnt(1)
	v_mfma_f32_16x16x32_bf16 v[156:159], v[76:79], v[56:59], 0
	ds_read_b128 v[76:79], v144 offset:6912
	s_waitcnt lgkmcnt(0)
	v_mfma_f32_16x16x32_bf16 v[160:163], v[76:79], v[56:59], 0
	ds_read_b128 v[76:79], v144 offset:16128
	v_mfma_f32_16x16x32_bf16 v[60:63], v[60:63], v[56:59], 0
	v_mfma_f32_16x16x32_bf16 v[64:67], v[64:67], v[56:59], 0
	v_mfma_f32_16x16x32_bf16 v[68:71], v[68:71], v[56:59], 0
	v_mfma_f32_16x16x32_bf16 v[72:75], v[72:75], v[56:59], 0
	s_waitcnt lgkmcnt(0)
	v_mfma_f32_16x16x32_bf16 v[164:167], v[76:79], v[56:59], 0
	ds_read_b128 v[168:171], v80 offset:18496
	ds_read_b128 v[56:59], v144 offset:64
	ds_read_b64 v[110:111], v145 offset:18432
	s_waitcnt lgkmcnt(1)
	v_mfma_f32_16x16x32_bf16 v[84:87], v[56:59], v[168:171], v[60:63]
	ds_read_b128 v[56:59], v144 offset:9280
	s_nop 1
	ds_read_b128 v[60:63], v144 offset:16192
	s_waitcnt lgkmcnt(1)
	v_mfma_f32_16x16x32_bf16 v[80:83], v[56:59], v[168:171], v[64:67]
	ds_read_b128 v[56:59], v144 offset:2368
	s_nop 0
	v_add_f32_e32 v84, v0, v84
	v_mul_f32_e32 v84, 0xbfb8aa3b, v84
	s_waitcnt lgkmcnt(0)
	v_mfma_f32_16x16x32_bf16 v[76:79], v[56:59], v[168:171], v[68:71]
	ds_read_b128 v[56:59], v144 offset:11584
	v_exp_f32_e32 v84, v84
	v_add_f32_e32 v80, v4, v80
	v_mul_f32_e32 v80, 0xbfb8aa3b, v80
	v_exp_f32_e32 v80, v80
	v_add_f32_e32 v84, 1.0, v84
	v_rcp_f32_e32 v107, v84
	s_waitcnt lgkmcnt(0)
	v_mfma_f32_16x16x32_bf16 v[72:75], v[56:59], v[168:171], v[72:75]
	ds_read_b128 v[56:59], v144 offset:4672
	v_add_f32_e32 v80, 1.0, v80
	v_mul_f32_e32 v107, v127, v107
	v_rcp_f32_e32 v84, v80
	v_mul_f32_e32 v80, 0x3fb8aa3b, v107
	v_add_f32_e32 v107, v107, v107
	v_mul_f32_e32 v107, 0x3fb8aa3b, v107
	v_add_f32_e32 v85, v1, v85
	v_exp_f32_e32 v107, v107
	v_mul_f32_e32 v85, 0xbfb8aa3b, v85
	v_exp_f32_e32 v85, v85
	v_add_f32_e32 v81, v5, v81
	v_sub_f32_e32 v107, 1.0, v107
	v_max_f32_e32 v107, 0, v107
	v_add_f32_e32 v85, 1.0, v85
	v_mul_f32_e32 v81, 0xbfb8aa3b, v81
	s_waitcnt lgkmcnt(0)
	v_mfma_f32_16x16x32_bf16 v[68:71], v[56:59], v[168:171], v[152:155]
	v_exp_f32_e32 v81, v81
	v_add_f32_e32 v86, v2, v86
	v_mul_f32_e32 v86, 0xbfb8aa3b, v86
	v_sqrt_f32_e32 v152, v107
	v_rcp_f32_e32 v107, v85
	v_add_f32_e32 v81, 1.0, v81
	v_rcp_f32_e32 v85, v81
	v_exp_f32_e32 v86, v86
	v_mul_f32_e32 v107, v126, v107
	v_mul_f32_e32 v81, 0x3fb8aa3b, v107
	v_add_f32_e32 v107, v107, v107
	v_mul_f32_e32 v107, 0x3fb8aa3b, v107
	v_exp_f32_e32 v107, v107
	v_add_f32_e32 v82, v6, v82
	v_add_f32_e32 v86, 1.0, v86
	v_mul_f32_e32 v82, 0xbfb8aa3b, v82
	v_sub_f32_e32 v107, 1.0, v107
	v_max_f32_e32 v107, 0, v107
	v_sqrt_f32_e32 v153, v107
	v_rcp_f32_e32 v107, v86
	v_exp_f32_e32 v82, v82
	v_add_f32_e32 v87, v3, v87
	v_mul_f32_e32 v87, 0xbfb8aa3b, v87
	v_mul_f32_e32 v107, v125, v107
	v_add_f32_e32 v82, 1.0, v82
	v_rcp_f32_e32 v86, v82
	v_mul_f32_e32 v82, 0x3fb8aa3b, v107
	v_add_f32_e32 v107, v107, v107
	v_mul_f32_e32 v107, 0x3fb8aa3b, v107
	v_exp_f32_e32 v107, v107
	v_exp_f32_e32 v87, v87
	v_add_f32_e32 v83, v7, v83
	v_mul_f32_e32 v83, 0xbfb8aa3b, v83
	v_sub_f32_e32 v107, 1.0, v107
	v_max_f32_e32 v107, 0, v107
	v_add_f32_e32 v87, 1.0, v87
	v_pk_mul_f32 v[84:85], v[84:85], v[152:153]
	v_sqrt_f32_e32 v152, v107
	v_rcp_f32_e32 v107, v87
	v_exp_f32_e32 v83, v83
	ds_read_b128 v[56:59], v144 offset:13888
	v_exp_f32_e32 v80, v80
	v_mul_f32_e32 v107, v124, v107
	v_add_f32_e32 v83, 1.0, v83
	v_rcp_f32_e32 v87, v83
	v_mul_f32_e32 v83, 0x3fb8aa3b, v107
	v_add_f32_e32 v107, v107, v107
	v_mul_f32_e32 v107, 0x3fb8aa3b, v107
	v_exp_f32_e32 v107, v107
	v_exp_f32_e32 v81, v81
	v_exp_f32_e32 v82, v82
	v_exp_f32_e32 v83, v83
	v_sub_f32_e32 v107, 1.0, v107
	v_max_f32_e32 v107, 0, v107
	v_sqrt_f32_e32 v153, v107
	v_add_f32_e32 v76, v8, v76
	v_add_f32_e32 v77, v9, v77
	v_mul_f32_e32 v76, 0xbfb8aa3b, v76
	v_mul_f32_e32 v77, 0xbfb8aa3b, v77
	v_exp_f32_e32 v76, v76
	v_exp_f32_e32 v77, v77
	v_lshlrev_b32_e32 v154, 16, v110
	v_and_b32_e32 v155, 0xffff0000, v110
	v_lshlrev_b32_e32 v110, 16, v111
	v_and_b32_e32 v111, 0xffff0000, v111
	v_pk_mul_f32 v[86:87], v[86:87], v[152:153]
	v_add_u32_e32 v107, v133, v137
	s_waitcnt lgkmcnt(0)
	v_mfma_f32_16x16x32_bf16 v[64:67], v[56:59], v[168:171], v[156:159]
	ds_read_b128 v[56:59], v144 offset:6976
	v_pk_mul_f32 v[84:85], v[84:85], v[154:155]
	v_pk_mul_f32 v[86:87], v[86:87], v[110:111]
	ds_write_b128 v107, v[80:83] offset:36864
	v_add_u32_e32 v80, v134, v137
	v_add_f32_e32 v78, v10, v78
	ds_write_b128 v80, v[84:87]
	v_add_f32_e32 v72, v12, v72
	v_add_f32_e32 v73, v13, v73
	v_mul_f32_e32 v78, 0xbfb8aa3b, v78
	ds_read_b64 v[80:81], v146 offset:18432
	v_add_f32_e32 v76, 1.0, v76
	v_mul_f32_e32 v72, 0xbfb8aa3b, v72
	v_add_f32_e32 v77, 1.0, v77
	v_mul_f32_e32 v73, 0xbfb8aa3b, v73
	v_exp_f32_e32 v78, v78
	v_rcp_f32_e32 v82, v76
	v_exp_f32_e32 v72, v72
	v_rcp_f32_e32 v83, v77
	v_exp_f32_e32 v73, v73
	v_add_f32_e32 v74, v14, v74
	v_add_f32_e32 v78, 1.0, v78
	v_mul_f32_e32 v74, 0xbfb8aa3b, v74
	v_add_f32_e32 v72, 1.0, v72
	v_mul_f32_e32 v82, v123, v82
	v_add_f32_e32 v73, 1.0, v73
	v_mul_f32_e32 v83, v122, v83
	s_waitcnt lgkmcnt(0)
	v_lshlrev_b32_e32 v84, 16, v80
	v_and_b32_e32 v85, 0xffff0000, v80
	v_rcp_f32_e32 v80, v78
	v_exp_f32_e32 v74, v74
	v_rcp_f32_e32 v76, v72
	v_mul_f32_e32 v72, 0x3fb8aa3b, v82
	v_add_f32_e32 v82, v82, v82
	v_rcp_f32_e32 v77, v73
	v_mul_f32_e32 v73, 0x3fb8aa3b, v83
	v_add_f32_e32 v83, v83, v83
	v_mul_f32_e32 v82, 0x3fb8aa3b, v82
	v_mul_f32_e32 v83, 0x3fb8aa3b, v83
	v_exp_f32_e32 v82, v82
	v_exp_f32_e32 v83, v83
	v_add_f32_e32 v74, 1.0, v74
	v_mul_f32_e32 v80, v121, v80
	v_rcp_f32_e32 v78, v74
	v_mul_f32_e32 v74, 0x3fb8aa3b, v80
	v_add_f32_e32 v80, v80, v80
	v_mul_f32_e32 v80, 0x3fb8aa3b, v80
	v_add_f32_e32 v79, v11, v79
	v_sub_f32_e32 v82, 1.0, v82
	v_sub_f32_e32 v83, 1.0, v83
	v_exp_f32_e32 v80, v80
	v_mul_f32_e32 v79, 0xbfb8aa3b, v79
	v_max_f32_e32 v82, 0, v82
	v_max_f32_e32 v83, 0, v83
	v_exp_f32_e32 v79, v79
	v_sqrt_f32_e32 v82, v82
	v_sqrt_f32_e32 v83, v83
	v_sub_f32_e32 v80, 1.0, v80
	v_add_f32_e32 v75, v15, v75
	v_max_f32_e32 v80, 0, v80
	v_add_f32_e32 v79, 1.0, v79
	v_mul_f32_e32 v75, 0xbfb8aa3b, v75
	v_pk_mul_f32 v[76:77], v[76:77], v[82:83]
	v_sqrt_f32_e32 v82, v80
	v_rcp_f32_e32 v80, v79
	v_exp_f32_e32 v75, v75
	v_exp_f32_e32 v72, v72
	v_exp_f32_e32 v73, v73
	v_mul_f32_e32 v80, v120, v80
	v_add_f32_e32 v75, 1.0, v75
	v_rcp_f32_e32 v79, v75
	v_mul_f32_e32 v75, 0x3fb8aa3b, v80
	v_add_f32_e32 v80, v80, v80
	v_mul_f32_e32 v80, 0x3fb8aa3b, v80
	v_exp_f32_e32 v80, v80
	v_exp_f32_e32 v74, v74
	v_exp_f32_e32 v75, v75
	v_add_f32_e32 v68, v16, v68
	v_sub_f32_e32 v80, 1.0, v80
	v_max_f32_e32 v80, 0, v80
	v_sqrt_f32_e32 v83, v80
	v_add_f32_e32 v69, v17, v69
	v_mul_f32_e32 v68, 0xbfb8aa3b, v68
	v_mul_f32_e32 v69, 0xbfb8aa3b, v69
	v_lshlrev_b32_e32 v80, 16, v81
	v_and_b32_e32 v81, 0xffff0000, v81
	v_pk_mul_f32 v[78:79], v[78:79], v[82:83]
	v_exp_f32_e32 v68, v68
	v_exp_f32_e32 v69, v69
	v_pk_mul_f32 v[78:79], v[78:79], v[80:81]
	v_add_u32_e32 v80, v133, v138
	v_pk_mul_f32 v[76:77], v[76:77], v[84:85]
	ds_write_b128 v80, v[72:75] offset:36864
	v_add_u32_e32 v72, v134, v138
	v_add_f32_e32 v70, v18, v70
	ds_write_b128 v72, v[76:79]
	v_add_f32_e32 v64, v20, v64
	v_add_f32_e32 v65, v21, v65
	v_mul_f32_e32 v70, 0xbfb8aa3b, v70
	ds_read_b64 v[72:73], v147 offset:18432
	v_add_f32_e32 v68, 1.0, v68
	v_mul_f32_e32 v64, 0xbfb8aa3b, v64
	v_add_f32_e32 v69, 1.0, v69
	v_mul_f32_e32 v65, 0xbfb8aa3b, v65
	v_exp_f32_e32 v70, v70
	v_rcp_f32_e32 v74, v68
	v_exp_f32_e32 v64, v64
	v_rcp_f32_e32 v75, v69
	v_exp_f32_e32 v65, v65
	v_add_f32_e32 v66, v22, v66
	v_add_f32_e32 v70, 1.0, v70
	v_mul_f32_e32 v66, 0xbfb8aa3b, v66
	v_add_f32_e32 v64, 1.0, v64
	v_mul_f32_e32 v74, v119, v74
	v_add_f32_e32 v65, 1.0, v65
	v_mul_f32_e32 v75, v118, v75
	s_waitcnt lgkmcnt(0)
	v_lshlrev_b32_e32 v76, 16, v72
	v_and_b32_e32 v77, 0xffff0000, v72
	v_rcp_f32_e32 v72, v70
	v_exp_f32_e32 v66, v66
	v_rcp_f32_e32 v68, v64
	v_mul_f32_e32 v64, 0x3fb8aa3b, v74
	v_add_f32_e32 v74, v74, v74
	v_rcp_f32_e32 v69, v65
	v_mul_f32_e32 v65, 0x3fb8aa3b, v75
	v_add_f32_e32 v75, v75, v75
	v_mul_f32_e32 v74, 0x3fb8aa3b, v74
	v_mul_f32_e32 v75, 0x3fb8aa3b, v75
	v_exp_f32_e32 v74, v74
	v_exp_f32_e32 v75, v75
	v_add_f32_e32 v66, 1.0, v66
	v_mul_f32_e32 v72, v117, v72
	v_rcp_f32_e32 v70, v66
	v_mul_f32_e32 v66, 0x3fb8aa3b, v72
	v_add_f32_e32 v72, v72, v72
	v_mul_f32_e32 v72, 0x3fb8aa3b, v72
	v_add_f32_e32 v71, v19, v71
	v_sub_f32_e32 v74, 1.0, v74
	v_sub_f32_e32 v75, 1.0, v75
	v_exp_f32_e32 v72, v72
	v_mul_f32_e32 v71, 0xbfb8aa3b, v71
	v_max_f32_e32 v74, 0, v74
	v_max_f32_e32 v75, 0, v75
	v_exp_f32_e32 v71, v71
	v_sqrt_f32_e32 v74, v74
	v_sqrt_f32_e32 v75, v75
	v_sub_f32_e32 v72, 1.0, v72
	v_add_f32_e32 v67, v23, v67
	v_max_f32_e32 v72, 0, v72
	v_add_f32_e32 v71, 1.0, v71
	v_mul_f32_e32 v67, 0xbfb8aa3b, v67
	v_pk_mul_f32 v[68:69], v[68:69], v[74:75]
	v_sqrt_f32_e32 v74, v72
	v_rcp_f32_e32 v72, v71
	v_exp_f32_e32 v67, v67
	v_mfma_f32_16x16x32_bf16 v[56:59], v[56:59], v[168:171], v[160:163]
	v_exp_f32_e32 v64, v64
	v_mul_f32_e32 v72, v116, v72
	v_add_f32_e32 v67, 1.0, v67
	v_rcp_f32_e32 v71, v67
	v_mul_f32_e32 v67, 0x3fb8aa3b, v72
	v_add_f32_e32 v72, v72, v72
	v_mul_f32_e32 v72, 0x3fb8aa3b, v72
	v_exp_f32_e32 v72, v72
	v_add_f32_e32 v56, v24, v56
	v_add_f32_e32 v57, v25, v57
	v_mul_f32_e32 v56, 0xbfb8aa3b, v56
	v_sub_f32_e32 v72, 1.0, v72
	v_max_f32_e32 v72, 0, v72
	v_mul_f32_e32 v57, 0xbfb8aa3b, v57
	v_sqrt_f32_e32 v75, v72
	v_exp_f32_e32 v56, v56
	v_exp_f32_e32 v57, v57
	v_exp_f32_e32 v65, v65
	v_exp_f32_e32 v66, v66
	v_exp_f32_e32 v67, v67
	v_add_f32_e32 v58, v26, v58
	v_mul_f32_e32 v58, 0xbfb8aa3b, v58
	v_lshlrev_b32_e32 v72, 16, v73
	v_and_b32_e32 v73, 0xffff0000, v73
	v_pk_mul_f32 v[70:71], v[70:71], v[74:75]
	v_add_f32_e32 v56, 1.0, v56
	v_add_f32_e32 v57, 1.0, v57
	v_exp_f32_e32 v58, v58
	v_pk_mul_f32 v[70:71], v[70:71], v[72:73]
	v_add_u32_e32 v72, v133, v139
	v_rcp_f32_e32 v56, v56
	v_rcp_f32_e32 v57, v57
	v_pk_mul_f32 v[68:69], v[68:69], v[76:77]
	ds_write_b128 v72, v[64:67] offset:36864
	v_add_u32_e32 v64, v134, v139
	v_mfma_f32_16x16x32_bf16 v[60:63], v[60:63], v[168:171], v[164:167]
	ds_write_b128 v64, v[68:71]
	ds_read_b64 v[64:65], v148 offset:18432
	v_add_f32_e32 v58, 1.0, v58
	v_mul_f32_e32 v66, v115, v56
	v_mul_f32_e32 v67, v114, v57
	v_rcp_f32_e32 v58, v58
	v_mul_f32_e32 v56, 0x3fb8aa3b, v66
	v_add_f32_e32 v66, v66, v66
	v_mul_f32_e32 v57, 0x3fb8aa3b, v67
	v_add_f32_e32 v67, v67, v67
	v_add_f32_e32 v60, v28, v60
	v_mul_f32_e32 v66, 0x3fb8aa3b, v66
	v_add_f32_e32 v61, v29, v61
	v_mul_f32_e32 v67, 0x3fb8aa3b, v67
	v_add_f32_e32 v59, v27, v59
	v_mul_f32_e32 v60, 0xbfb8aa3b, v60
	v_exp_f32_e32 v66, v66
	v_mul_f32_e32 v61, 0xbfb8aa3b, v61
	v_exp_f32_e32 v67, v67
	v_mul_f32_e32 v59, 0xbfb8aa3b, v59
	v_exp_f32_e32 v60, v60
	v_exp_f32_e32 v61, v61
	s_waitcnt lgkmcnt(0)
	v_lshlrev_b32_e32 v68, 16, v64
	v_and_b32_e32 v69, 0xffff0000, v64
	v_mul_f32_e32 v64, v89, v58
	v_exp_f32_e32 v59, v59
	v_mul_f32_e32 v58, 0x3fb8aa3b, v64
	v_add_f32_e32 v64, v64, v64
	v_mul_f32_e32 v64, 0x3fb8aa3b, v64
	v_sub_f32_e32 v66, 1.0, v66
	v_sub_f32_e32 v67, 1.0, v67
	v_exp_f32_e32 v64, v64
	v_add_f32_e32 v60, 1.0, v60
	v_max_f32_e32 v66, 0, v66
	v_add_f32_e32 v61, 1.0, v61
	v_max_f32_e32 v67, 0, v67
	v_add_f32_e32 v59, 1.0, v59
	v_rcp_f32_e32 v60, v60
	v_sqrt_f32_e32 v66, v66
	v_rcp_f32_e32 v61, v61
	v_sqrt_f32_e32 v67, v67
	v_rcp_f32_e32 v59, v59
	v_sub_f32_e32 v64, 1.0, v64
	v_max_f32_e32 v64, 0, v64
	v_pk_mul_f32 v[60:61], v[60:61], v[66:67]
	v_sqrt_f32_e32 v66, v64
	v_mul_f32_e32 v64, v128, v59
	v_mul_f32_e32 v59, 0x3fb8aa3b, v64
	v_add_f32_e32 v64, v64, v64
	v_add_f32_e32 v62, v30, v62
	v_add_f32_e32 v63, v31, v63
	v_mul_f32_e32 v64, 0x3fb8aa3b, v64
	v_mul_f32_e32 v62, 0xbfb8aa3b, v62
	v_mul_f32_e32 v63, 0xbfb8aa3b, v63
	v_exp_f32_e32 v64, v64
	v_exp_f32_e32 v62, v62
	v_exp_f32_e32 v63, v63
	v_exp_f32_e32 v56, v56
	v_sub_f32_e32 v64, 1.0, v64
	v_add_f32_e32 v62, 1.0, v62
	v_add_f32_e32 v63, 1.0, v63
	v_max_f32_e32 v64, 0, v64
	v_rcp_f32_e32 v62, v62
	v_rcp_f32_e32 v63, v63
	v_sqrt_f32_e32 v67, v64
	v_exp_f32_e32 v57, v57
	v_exp_f32_e32 v58, v58
	v_exp_f32_e32 v59, v59
	v_lshlrev_b32_e32 v64, 16, v65
	v_and_b32_e32 v65, 0xffff0000, v65
	v_pk_mul_f32 v[62:63], v[62:63], v[66:67]
	v_pk_mul_f32 v[60:61], v[60:61], v[68:69]
	v_pk_mul_f32 v[62:63], v[62:63], v[64:65]
	v_add_u32_e32 v64, v133, v140
	ds_write_b128 v64, v[56:59] offset:36864
	v_add_u32_e32 v56, v134, v140
	v_lshl_add_u64 v[66:67], s[0:1], 0, v[108:109]
	ds_write_b128 v56, v[60:63]
	v_add_co_u32_e32 v56, vcc, s16, v66
	s_waitcnt lgkmcnt(0)
	s_barrier
	s_nop 0
	v_addc_co_u32_e32 v57, vcc, 0, v67, vcc
	global_load_ushort v163, v108, s[0:1] offset:2048
	global_load_ushort v162, v[56:57], off offset:3072
	s_movk_i32 s0, 0x5000
	v_add_co_u32_e32 v56, vcc, s0, v66
	s_movk_i32 s0, 0x7000
	s_nop 0
	v_addc_co_u32_e32 v57, vcc, 0, v67, vcc
	global_load_ushort v161, v[56:57], off
	v_add_co_u32_e32 v56, vcc, s0, v66
	s_mov_b32 s0, 0x9000
	s_nop 0
	v_addc_co_u32_e32 v57, vcc, 0, v67, vcc
	global_load_ushort v160, v[56:57], off offset:1024
	v_add_co_u32_e32 v56, vcc, s0, v66
	s_mov_b32 s0, 0xb000
	s_nop 0
	v_addc_co_u32_e32 v57, vcc, 0, v67, vcc
	global_load_ushort v159, v[56:57], off offset:2048
	v_add_co_u32_e32 v56, vcc, s0, v66
	s_mov_b32 s0, 0xe000
	s_nop 0
	v_addc_co_u32_e32 v57, vcc, 0, v67, vcc
	global_load_ushort v158, v[56:57], off offset:3072
	v_add_co_u32_e32 v56, vcc, s0, v66
	s_mov_b32 s0, 0x10000
	s_nop 0
	v_addc_co_u32_e32 v57, vcc, 0, v67, vcc
	global_load_ushort v157, v[56:57], off
	v_add_co_u32_e32 v56, vcc, s0, v66
	s_mov_b32 s0, 0x12000
	s_nop 0
	v_addc_co_u32_e32 v57, vcc, 0, v67, vcc
	global_load_ushort v156, v[56:57], off offset:1024
	v_add_co_u32_e32 v56, vcc, s0, v66
	s_mov_b32 s0, 0x14000
	s_nop 0
	v_addc_co_u32_e32 v57, vcc, 0, v67, vcc
	global_load_ushort v155, v[56:57], off offset:2048
	v_add_co_u32_e32 v56, vcc, s0, v66
	s_mov_b32 s0, 0x17000
	s_nop 0
	v_addc_co_u32_e32 v57, vcc, 0, v67, vcc
	global_load_ushort v154, v[56:57], off offset:3072
	v_add_co_u32_e32 v56, vcc, s0, v66
	s_mov_b32 s0, 0x19000
	s_nop 0
	v_addc_co_u32_e32 v57, vcc, 0, v67, vcc
	global_load_ushort v153, v[56:57], off
	v_add_co_u32_e32 v56, vcc, s0, v66
	s_mov_b32 s0, 0x1b000
	s_nop 0
	v_addc_co_u32_e32 v57, vcc, 0, v67, vcc
	global_load_ushort v152, v[56:57], off offset:1024
	v_add_co_u32_e32 v56, vcc, s0, v66
	s_mov_b32 s0, 0x1d000
	s_nop 0
	v_addc_co_u32_e32 v57, vcc, 0, v67, vcc
	global_load_ushort v151, v[56:57], off offset:2048
	v_add_co_u32_e32 v56, vcc, s0, v66
	s_mov_b32 s0, 0x20000
	s_nop 0
	v_addc_co_u32_e32 v57, vcc, 0, v67, vcc
	global_load_ushort v112, v[56:57], off offset:3072
	v_add_co_u32_e32 v56, vcc, s0, v66
	s_mov_b32 s0, 0x22000
	s_nop 0
	v_addc_co_u32_e32 v57, vcc, 0, v67, vcc
	global_load_ushort v109, v[56:57], off
	v_add_co_u32_e32 v56, vcc, s0, v66
	v_add_u32_e32 v62, 0x9000, v149
	s_nop 0
	v_addc_co_u32_e32 v57, vcc, 0, v67, vcc
	global_load_ushort v107, v[56:57], off offset:1024
	ds_read_b32 v182, v149 offset:36864
	ds_read_b32 v166, v150
	ds_read_b32 v183, v149 offset:37136
	ds_read_b32 v167, v150 offset:272
	ds_read_b32 v184, v149 offset:37408
	ds_read_b32 v168, v150 offset:544
	ds_read_b32 v185, v149 offset:37680
	ds_read_b32 v169, v150 offset:816
	ds_read_b32 v186, v149 offset:37952
	ds_read_b32 v170, v150 offset:1088
	ds_read_b32 v187, v149 offset:38224
	ds_read_b32 v171, v150 offset:1360
	ds_read_b32 v188, v149 offset:38496
	ds_read_b32 v172, v150 offset:1632
	ds_read_b32 v189, v149 offset:38768
	ds_read_b32 v173, v150 offset:1904
	ds_read_b32 v208, v149 offset:39040
	ds_read_b32 v174, v150 offset:2176
	ds_read_b32 v209, v149 offset:39312
	ds_read_b32 v175, v150 offset:2448
	ds_read_b32 v210, v149 offset:39584
	ds_read_b32 v176, v150 offset:2720
	ds_read_b32 v211, v149 offset:39856
	ds_read_b32 v177, v150 offset:2992
	ds_read_b32 v212, v149 offset:40128
	ds_read_b32 v178, v150 offset:3264
	ds_read_b32 v213, v149 offset:40400
	ds_read_b32 v179, v150 offset:3536
	ds_read_b32 v252, v149 offset:40672
	ds_read_b32 v180, v150 offset:3808
	ds_read_b32 v253, v149 offset:40944
	ds_read_b32 v181, v150 offset:4080
	s_lshl_b32 s0, s11, 6
	s_and_b32 s0, s0, 64
	s_andn2_b64 vcc, exec, s[4:5]
	s_mov_b32 s1, s10
	s_waitcnt lgkmcnt(0)
	v_fma_f32 v166, 0, v182, v166
	v_fma_f32 v167, v166, v183, v167
	v_mul_f32_e32 v183, v182, v183
	v_fma_f32 v168, v167, v184, v168
	v_mul_f32_e32 v184, v183, v184
	v_fma_f32 v169, v168, v185, v169
	v_mul_f32_e32 v185, v184, v185
	v_fma_f32 v170, v169, v186, v170
	v_mul_f32_e32 v186, v185, v186
	v_fma_f32 v171, v170, v187, v171
	v_mul_f32_e32 v187, v186, v187
	v_fma_f32 v172, v171, v188, v172
	v_mul_f32_e32 v188, v187, v188
	v_fma_f32 v173, v172, v189, v173
	v_mul_f32_e32 v189, v188, v189
	v_fma_f32 v174, v173, v208, v174
	v_mul_f32_e32 v208, v189, v208
	v_fma_f32 v175, v174, v209, v175
	v_mul_f32_e32 v209, v208, v209
	v_fma_f32 v176, v175, v210, v176
	v_mul_f32_e32 v210, v209, v210
	v_fma_f32 v177, v176, v211, v177
	v_mul_f32_e32 v211, v210, v211
	v_fma_f32 v178, v177, v212, v178
	v_mul_f32_e32 v212, v211, v212
	v_fma_f32 v179, v178, v213, v179
	v_mul_f32_e32 v213, v212, v213
	v_fma_f32 v180, v179, v252, v180
	v_mul_f32_e32 v252, v213, v252
	v_fma_f32 v181, v180, v253, v181
	v_mul_f32_e32 v253, v252, v253
	ds_write_b32 v150, v166
	ds_write_b32 v150, v167 offset:272
	ds_write_b32 v149, v183 offset:37136
	ds_write_b32 v150, v168 offset:544
	ds_write_b32 v149, v184 offset:37408
	ds_write_b32 v150, v169 offset:816
	ds_write_b32 v149, v185 offset:37680
	ds_write_b32 v150, v170 offset:1088
	ds_write_b32 v149, v186 offset:37952
	ds_write_b32 v150, v171 offset:1360
	ds_write_b32 v149, v187 offset:38224
	ds_write_b32 v150, v172 offset:1632
	ds_write_b32 v149, v188 offset:38496
	ds_write_b32 v150, v173 offset:1904
	ds_write_b32 v149, v189 offset:38768
	ds_write_b32 v150, v174 offset:2176
	ds_write_b32 v149, v208 offset:39040
	ds_write_b32 v150, v175 offset:2448
	ds_write_b32 v149, v209 offset:39312
	ds_write_b32 v150, v176 offset:2720
	ds_write_b32 v149, v210 offset:39584
	ds_write_b32 v150, v177 offset:2992
	ds_write_b32 v149, v211 offset:39856
	ds_write_b32 v150, v178 offset:3264
	ds_write_b32 v149, v212 offset:40128
	ds_write_b32 v150, v179 offset:3536
	ds_write_b32 v149, v213 offset:40400
	ds_write_b32 v150, v180 offset:3808
	ds_write_b32 v149, v252 offset:40672
	ds_write_b32 v150, v181 offset:4080
	v_mov_b32_e32 v164, v253
	v_mov_b32_e32 v111, v181
	ds_write_b32 v149, v164 offset:40944
	ds_write_b32 v135, v164
	ds_write_b32 v136, v111
	s_waitcnt lgkmcnt(0)
	s_barrier
	ds_read_b32 v166, v150
	ds_read_b32 v182, v149 offset:36864
	ds_read_b32 v167, v150 offset:272
	ds_read_b32 v183, v149 offset:37136
	ds_read_b32 v168, v150 offset:544
	ds_read_b32 v184, v149 offset:37408
	ds_read_b32 v169, v150 offset:816
	ds_read_b32 v185, v149 offset:37680
	ds_read_b32 v170, v150 offset:1088
	ds_read_b32 v186, v149 offset:37952
	ds_read_b32 v171, v150 offset:1360
	ds_read_b32 v187, v149 offset:38224
	ds_read_b32 v172, v150 offset:1632
	ds_read_b32 v188, v149 offset:38496
	ds_read_b32 v173, v150 offset:1904
	ds_read_b32 v189, v149 offset:38768
	ds_read_b32 v174, v150 offset:2176
	ds_read_b32 v208, v149 offset:39040
	ds_read_b32 v175, v150 offset:2448
	ds_read_b32 v209, v149 offset:39312
	ds_read_b32 v176, v150 offset:2720
	ds_read_b32 v210, v149 offset:39584
	ds_read_b32 v177, v150 offset:2992
	ds_read_b32 v211, v149 offset:39856
	ds_read_b32 v178, v150 offset:3264
	ds_read_b32 v212, v149 offset:40128
	ds_read_b32 v179, v150 offset:3536
	ds_read_b32 v213, v149 offset:40400
	ds_read_b32 v180, v150 offset:3808
	ds_read_b32 v252, v149 offset:40672
	ds_read_b32 v181, v150 offset:4080
	ds_read_b32 v253, v149 offset:40944
	v_lshl_add_u32 v56, s0, 2, v129
	ds_read_b32 v110, v56
	v_mov_b32_e32 v56, v141
	s_cbranch_vccnz .LBB0_1096
